# scan: odd chunk's loads waited for one iteration later (counted waits; last iteration waits for everything where it skips the even loads)
# speedup vs baseline: 1.0106x; 1.0106x over previous
.LBB0_575:
	s_or_b64 exec, exec, s[2:3]
	s_lshl_b32 s64, s96, 3
	s_and_b32 s0, s64, 56
	s_lshr_b32 s1, s96, 5
	s_add_i32 s34, s0, s1
	s_lshl_b32 s4, s34, 5
	s_mov_b32 s7, 0
	s_lshr_b32 s2, s34, 3
	s_bfe_u32 s0, s96, 0x30005
	s_mov_b32 s5, s7
	s_mov_b32 s3, s7
	s_or_b32 s6, s4, 1
	s_bfe_u32 s65, s96, 0x20003
	s_lshl_b64 s[8:9], s[4:5], 14
	s_lshl_b64 s[36:37], s[2:3], 11
	s_lshl_b64 s[12:13], s[6:7], 14
	s_lshl_b32 s6, s0, 7
	v_mov_b32_e32 v56, v198
	s_waitcnt lgkmcnt(0)
	s_barrier
	s_mov_b32 s35, s7
	s_add_u32 s10, s82, s8
	s_waitcnt vmcnt(2)
	v_ashrrev_i32_e32 v58, 3, v56
	s_addc_u32 s11, s83, s9
	s_lshl_b64 s[8:9], s[34:35], 19
	v_ashrrev_i32_e32 v59, 31, v58
	s_add_u32 s14, s42, s8
	v_add_u32_e32 v62, 0x200, v56
	v_lshl_add_u64 v[24:25], s[36:37], 0, v[58:59]
	v_ashrrev_i32_e32 v57, 31, v56
	s_addc_u32 s15, s43, s9
	v_ashrrev_i32_e32 v63, 31, v62
	v_lshlrev_b64 v[24:25], 12, v[24:25]
	v_and_b32_e32 v84, 15, v56
	v_lshlrev_b64 v[64:65], 3, v[56:57]
	v_lshlrev_b64 v[60:61], 4, v[56:57]
	s_add_u32 s16, s44, s8
	s_waitcnt vmcnt(1)
	v_lshlrev_b64 v[66:67], 3, v[62:63]
	v_lshlrev_b64 v[80:81], 4, v[62:63]
	v_lshl_add_u64 v[24:25], s[50:51], 0, v[24:25]
	v_lshlrev_b32_e32 v57, 4, v56
	v_mov_b32_e32 v69, 0
	v_ashrrev_i32_e32 v63, 2, v56
	s_addc_u32 s17, s45, s9
	v_lshl_add_u64 v[24:25], v[24:25], 0, s[6:7]
	s_waitcnt vmcnt(0)
	v_and_b32_e32 v72, 0x70, v57
	v_mov_b32_e32 v73, v69
	v_and_or_b32 v82, v63, 16, v84
	v_lshl_add_u64 v[0:1], s[10:11], 0, v[60:61]
	v_lshl_add_u64 v[12:13], s[10:11], 0, v[80:81]
	v_lshl_add_u64 v[52:53], v[24:25], 0, v[72:73]
	s_add_u32 s10, s46, s8
	v_lshlrev_b32_e32 v24, 7, v82
	s_addc_u32 s11, s47, s9
	v_lshl_or_b32 v74, s65, 12, v24
	v_mov_b32_e32 v75, v69
	v_lshl_add_u64 v[24:25], s[10:11], 0, v[74:75]
	s_lshl_b64 s[10:11], s[4:5], 2
	s_add_u32 s10, s80, s10
	s_addc_u32 s11, s81, s11
	v_and_b32_e32 v86, -16, v58
	s_add_u32 s12, s82, s12
	v_ashrrev_i32_e32 v87, 31, v86
	s_addc_u32 s13, s83, s13
	s_or_b32 s5, s8, 0x4000
	v_bfe_u32 v79, v56, 4, 2
	v_lshl_add_u64 v[4:5], s[14:15], 0, v[60:61]
	v_lshl_add_u64 v[16:17], s[14:15], 0, v[80:81]
	v_lshlrev_b64 v[76:77], 1, v[86:87]
	s_add_u32 s14, s42, s5
	v_lshl_add_u64 v[24:25], v[24:25], 0, v[76:77]
	v_lshlrev_b32_e32 v68, 3, v79
	s_addc_u32 s15, s43, s9
	v_lshl_add_u64 v[8:9], s[16:17], 0, v[60:61]
	v_lshl_add_u64 v[20:21], s[16:17], 0, v[80:81]
	v_lshl_add_u64 v[24:25], v[24:25], 0, v[68:69]
	s_add_u32 s16, s44, s5
	global_load_dwordx2 v[92:93], v[24:25], off
	v_lshl_add_u64 v[24:25], s[12:13], 0, v[60:61]
	s_addc_u32 s17, s45, s9
	v_lshl_add_u64 v[40:41], s[12:13], 0, v[80:81]
	s_mov_b32 s12, 0x40000
	global_load_dwordx4 v[28:31], v[52:53], off
	v_add_co_u32_e32 v52, vcc, s12, v52
	s_add_u32 s12, s46, s5
	s_addc_u32 s13, s47, s9
	v_lshl_add_u64 v[70:71], s[12:13], 0, v[74:75]
	v_lshl_add_u64 v[70:71], v[70:71], 0, v[76:77]
	v_lshl_add_u64 v[32:33], s[14:15], 0, v[60:61]
	v_lshl_add_u64 v[36:37], s[16:17], 0, v[60:61]
	v_lshl_add_u64 v[44:45], s[14:15], 0, v[80:81]
	v_lshl_add_u64 v[48:49], s[16:17], 0, v[80:81]
	v_addc_co_u32_e32 v53, vcc, 0, v53, vcc
	v_lshl_add_u64 v[70:71], v[70:71], 0, v[68:69]
	global_load_dwordx4 v[0:3], v[0:1], off
	v_and_b32_e32 v73, -16, v63
	global_load_dwordx4 v[4:7], v[4:5], off
	v_mul_u32_u24_e32 v85, 0x88, v84
	global_load_dwordx4 v[8:11], v[8:9], off
	v_lshlrev_b32_e32 v85, 1, v85
	global_load_dwordx4 v[12:15], v[12:13], off
	v_lshlrev_b32_e32 v73, 1, v73
	global_load_dwordx4 v[16:19], v[16:17], off
	v_add3_u32 v90, 0, v85, v73
	global_load_dwordx4 v[20:23], v[20:21], off
	s_mov_b32 s13, 0xf400
	global_load_dwordx4 v[24:27], v[24:25], off
	v_mul_u32_u24_e32 v97, 0x48, v84
	global_load_dwordx4 v[32:35], v[32:33], off
	v_lshrrev_b32_e32 v78, 4, v56
	global_load_dwordx4 v[36:39], v[36:37], off
	s_movk_i32 s5, 0x110
	global_load_dwordx4 v[40:43], v[40:41], off
	v_lshrrev_b32_e32 v83, 4, v62
	global_load_dwordx4 v[44:47], v[44:45], off
	v_add3_u32 v108, v90, v68, s13
	global_load_dwordx4 v[48:51], v[48:49], off
	v_bfi_b32 v90, -16, v58, v56
	global_load_dwordx4 v[52:55], v[52:53], off
	s_nop 0
	global_load_dwordx2 v[88:89], v[70:71], off
	s_nop 0
	global_load_dwordx2 v[70:71], v69, s[10:11]
	v_mul_u32_u24_e32 v94, 0x88, v82
	v_mul_u32_u24_e32 v82, 0x48, v82
	v_lshlrev_b32_e32 v97, 1, v97
	v_mul_lo_u32 v75, v78, s5
	v_mul_lo_u32 v83, v83, s5
	v_mul_lo_u32 v91, v90, s5
	v_lshlrev_b32_e32 v79, 4, v79
	v_lshlrev_b32_e32 v82, 1, v82
	s_add_i32 s5, 0, 0x11600
	v_add_u32_e32 v99, 0x900, v97
	v_and_b32_e32 v57, 0xf0, v57
	v_add_u32_e32 v95, s5, v82
	v_add_u32_e32 v98, s5, v79
	v_add3_u32 v117, s5, v99, v79
	s_add_i32 s5, 0, 0x12800
	v_lshlrev_b32_e32 v96, 1, v86
	v_add3_u32 v118, s5, v75, v57
	s_add_i32 s13, 0, 0x16c00
	s_add_i32 s14, 0, 0x1b000
	v_add3_u32 v121, s5, v83, v57
	s_add_i32 s15, 0, 0x1f800
	s_add_i32 s16, 0, 0x21c00
	v_add3_u32 v127, s5, v91, v79
	s_add_i32 s5, 0, 0x23e00
	v_add3_u32 v104, 0, v75, v57
	s_movk_i32 s12, 0x90
	v_add3_u32 v106, 0, v83, v57
	v_add3_u32 v109, 0, v91, v79
	v_add3_u32 v111, v95, v96, v68
	v_add_u32_e32 v112, v95, v79
	v_lshlrev_b32_e32 v95, 7, v90
	v_add3_u32 v119, s13, v75, v57
	v_add3_u32 v122, s13, v83, v57
	v_add_u32_e32 v57, s16, v73
	s_add_u32 s10, s10, 12
	v_mul_lo_u32 v78, v58, s12
	v_sub_u32_e32 v113, v109, v95
	v_bfi_b32 v95, -16, v63, v56
	v_add3_u32 v125, v57, v68, v85
	v_add_u32_e32 v57, s5, v82
	s_addc_u32 s11, s11, 0
	s_lshl_b64 s[28:29], s[2:3], 23
	v_lshlrev_b64 v[58:59], 12, v[58:59]
	v_and_b32_e32 v56, 7, v56
	v_add3_u32 v129, v57, v96, v68
	v_add_u32_e32 v131, v57, v79
	v_mul_lo_u32 v57, v90, s12
	v_lshl_add_u64 v[58:59], s[28:29], 0, v[58:59]
	v_lshlrev_b32_e32 v56, 4, v56
	v_lshrrev_b32_e32 v62, 3, v62
	v_add3_u32 v132, s15, v57, v79
	v_add_u32_e32 v57, s5, v79
	v_or3_b32 v58, v58, s6, v56
	v_mul_lo_u32 v62, v62, s12
	v_mul_lo_u32 v95, v95, s12
	v_add3_u32 v130, s13, v91, v79
	v_add_u32_e32 v134, v57, v97
	v_add_u32_e32 v135, v57, v99
	v_lshl_add_u64 v[56:57], s[50:51], 0, v[58:59]
	s_mov_b64 s[12:13], 0xc0000
	v_add3_u32 v105, 0, v78, v72
	v_add3_u32 v107, 0, v62, v72
	v_add3_u32 v120, s14, v78, v72
	v_add3_u32 v123, s14, v62, v72
	v_add3_u32 v124, s15, v78, v72
	v_lshl_add_u64 v[72:73], v[56:57], 0, s[12:13]
	v_or_b32_e32 v56, v74, v68
	v_mov_b32_e32 v57, v69
	v_lshl_add_u64 v[56:57], v[56:57], 0, v[76:77]
	v_or_b32_e32 v86, v86, v84
	v_lshl_add_u64 v[74:75], s[46:47], 0, v[56:57]
	s_lshl_b64 s[30:31], s[2:3], 22
	v_lshlrev_b64 v[56:57], 11, v[86:87]
	v_add3_u32 v136, s5, v99, v79
	v_lshl_add_u64 v[56:57], s[30:31], 0, v[56:57]
	s_lshl_b32 s5, s0, 8
	v_lshlrev_b32_e32 v58, 1, v63
	v_or_b32_e32 v56, s5, v56
	s_lshl_b32 s6, s65, 6
	v_and_b32_e32 v58, 32, v58
	v_or3_b32 v56, v56, s6, v58
	v_lshl_add_u64 v[56:57], s[48:49], 0, v[56:57]
	s_mov_b64 s[12:13], 0x20000
	v_lshl_add_u64 v[84:85], v[56:57], 0, s[12:13]
	v_lshl_add_u64 v[56:57], v[86:87], 0, s[36:37]
	v_lshlrev_b64 v[56:57], 11, v[56:57]
	v_or_b32_e32 v56, s5, v56
	v_lshlrev_b32_e32 v94, 1, v94
	v_or3_b32 v56, v56, s6, v58
	v_add3_u32 v110, 0, v94, v79
	v_add3_u32 v114, 0, v95, v79
	v_add_u32_e32 v115, v98, v97
	v_add_u32_e32 v116, v98, v99
	v_add_u32_e32 v126, 0x1100, v125
	v_add3_u32 v128, s16, v94, v79
	v_add3_u32 v133, s14, v95, v79
	v_lshl_add_u64 v[76:77], s[44:45], 0, v[80:81]
	v_lshl_add_u64 v[78:79], s[44:45], 0, v[60:61]
	v_lshl_add_u64 v[80:81], s[42:43], 0, v[80:81]
	v_lshl_add_u64 v[82:83], s[42:43], 0, v[60:61]
	v_lshl_add_u64 v[86:87], s[48:49], 0, v[56:57]
	s_mov_b64 s[12:13], 0x80000
	s_mov_b64 s[14:15], 0x8000
	s_mov_b64 s[16:17], 0x40000
	s_mov_b32 s5, 0
	v_mov_b32_e32 v56, v69
	v_mov_b32_e32 v57, v69
	v_mov_b32_e32 v58, v69
	v_mov_b32_e32 v59, v69
	v_mov_b32_e32 v60, v69
	v_mov_b32_e32 v61, v69
	v_mov_b32_e32 v62, v69
	v_mov_b32_e32 v63, v69
	s_waitcnt vmcnt(0)
	v_mov_b32_e32 v137, v70
	v_mov_b64_e32 v[90:91], v[92:93]
	v_mov_b64_e32 v[172:173], v[88:89]
	v_mov_b32_e32 v174, v71
	s_branch .LBB0_577
.LBB0_576:
	ds_read_b128 v[94:97], v127
	ds_read_b128 v[140:143], v128
	ds_read_b128 v[146:149], v127 offset:64
	v_lshlrev_b32_e32 v98, 16, v88
	v_and_b32_e32 v99, 0xffff0000, v88
	v_lshlrev_b32_e32 v100, 16, v89
	v_and_b32_e32 v101, 0xffff0000, v89
	ds_read_b128 v[150:153], v128 offset:64
	v_pk_mul_f32 v[60:61], v[70:71], v[60:61] op_sel:[1,0]
	v_pk_mul_f32 v[62:63], v[70:71], v[62:63] op_sel:[1,0]
	s_waitcnt lgkmcnt(2)
	v_mfma_f32_16x16x32_bf16 v[94:97], v[94:97], v[140:143], v[98:101]
	s_nop 2
	ds_read_b128 v[98:101], v127 offset:128
	ds_read_b128 v[140:143], v127 offset:192
	v_pk_mul_f32 v[56:57], v[70:71], v[56:57] op_sel:[1,0]
	v_pk_mul_f32 v[58:59], v[70:71], v[58:59] op_sel:[1,0]
	s_waitcnt lgkmcnt(2)
	v_mfma_f32_16x16x32_bf16 v[94:97], v[146:149], v[150:153], v[94:97]
	ds_read_b128 v[146:149], v128 offset:128
	ds_read_b128 v[150:153], v128 offset:192
	s_add_i32 s5, s5, 2
	s_add_u32 s10, s10, 8
	s_waitcnt lgkmcnt(1)
	v_mfma_f32_16x16x32_bf16 v[94:97], v[98:101], v[146:149], v[94:97]
	v_lshl_add_u64 v[72:73], v[72:73], 0, s[12:13]
	v_lshl_add_u64 v[74:75], v[74:75], 0, s[14:15]
	v_lshl_add_u64 v[76:77], v[76:77], 0, s[14:15]
	s_waitcnt lgkmcnt(0)
	v_mfma_f32_16x16x32_bf16 v[94:97], v[140:143], v[150:153], v[94:97]
	v_lshl_add_u64 v[78:79], v[78:79], 0, s[14:15]
	v_lshl_add_u64 v[80:81], v[80:81], 0, s[14:15]
	v_lshl_add_u64 v[82:83], v[82:83], 0, s[14:15]
	v_lshl_add_u64 v[86:87], v[86:87], 0, s[16:17]
	s_addc_u32 s11, s11, 0
	s_nop 2
	v_cvt_pk_bf16_f32 v88, v94, v95
	v_cvt_pk_bf16_f32 v89, v96, v97
	ds_write_b64 v129, v[88:89]
	s_waitcnt lgkmcnt(0)
	s_barrier
	ds_read_b128 v[94:97], v128
	ds_read_b128 v[98:101], v130
	ds_read_b128 v[140:143], v128 offset:64
	ds_read_b128 v[146:149], v130 offset:64
	s_waitcnt lgkmcnt(2)
	v_mfma_f32_16x16x32_bf16 v[94:97], v[94:97], v[98:101], 0
	ds_read_b128 v[98:101], v128 offset:128
	ds_read_b128 v[150:153], v130 offset:128
	ds_read_b128 v[158:161], v128 offset:192
	v_lshl_add_u64 v[88:89], v[84:85], 0, v[68:69]
	v_lshl_add_u64 v[84:85], v[84:85], 0, s[16:17]
	s_waitcnt lgkmcnt(3)
	v_mfma_f32_16x16x32_bf16 v[94:97], v[140:143], v[146:149], v[94:97]
	ds_read_b128 v[140:143], v130 offset:192
	ds_read_b128 v[146:149], v131
	s_andn2_b64 vcc, exec, s[18:19]
	s_waitcnt lgkmcnt(3)
	v_mfma_f32_16x16x32_bf16 v[94:97], v[98:101], v[150:153], v[94:97]
	ds_read_b128 v[98:101], v132
	ds_read_b128 v[150:153], v131 offset:64
	s_waitcnt lgkmcnt(3)
	v_mfma_f32_16x16x32_bf16 v[94:97], v[158:161], v[140:143], v[94:97]
	ds_read_b128 v[140:143], v132 offset:64
	s_waitcnt lgkmcnt(2)
	v_mfma_f32_16x16x32_bf16 v[94:97], v[146:149], v[98:101], v[94:97]
	s_waitcnt lgkmcnt(0)
	v_mfma_f32_16x16x32_bf16 v[94:97], v[150:153], v[140:143], v[94:97]
	s_nop 7
	v_cvt_pk_bf16_f32 v70, v94, v95
	v_cvt_pk_bf16_f32 v71, v96, v97
	global_store_dwordx2 v[88:89], v[70:71], off sc1
	ds_read_b128 v[94:97], v133
	ds_read_b128 v[98:101], v134
	ds_read_b128 v[140:143], v133 offset:64
	ds_read_b128 v[146:149], v134 offset:64
	ds_read_b128 v[150:153], v135
	s_waitcnt lgkmcnt(3)
	v_mfma_f32_16x16x32_bf16 v[60:63], v[94:97], v[98:101], v[60:63]
	ds_read_b128 v[98:101], v136 offset:64
	s_waitcnt vmcnt(9)

	v_mov_b64_e32 v[92:93], v[90:91]
	s_waitcnt lgkmcnt(1)
	v_mfma_f32_16x16x32_bf16 v[56:59], v[94:97], v[150:153], v[56:59]
	v_mov_b32_e32 v70, v137


	v_mfma_f32_16x16x32_bf16 v[60:63], v[140:143], v[146:149], v[60:63]
	s_waitcnt lgkmcnt(0)
	v_mfma_f32_16x16x32_bf16 v[56:59], v[140:143], v[98:101], v[56:59]
	s_cbranch_vccz .LBB0_581

.LBB0_579:
	ds_read_b128 v[138:141], v109
	ds_read_b128 v[150:153], v110 offset:62464
	ds_read_b128 v[158:161], v109 offset:64
	v_lshlrev_b32_e32 v146, 16, v92
	v_and_b32_e32 v147, 0xffff0000, v92
	v_lshlrev_b32_e32 v148, 16, v93
	v_and_b32_e32 v149, 0xffff0000, v93
	ds_read_b128 v[168:171], v110 offset:62528
	v_pk_mul_f32 v[62:63], v[70:71], v[62:63] op_sel_hi:[0,1]
	v_pk_mul_f32 v[60:61], v[70:71], v[60:61] op_sel_hi:[0,1]
	s_waitcnt lgkmcnt(2)
	v_mfma_f32_16x16x32_bf16 v[138:141], v[138:141], v[150:153], v[146:149]
	s_nop 2
	ds_read_b128 v[146:149], v109 offset:128
	ds_read_b128 v[150:153], v109 offset:192
	v_pk_mul_f32 v[58:59], v[70:71], v[58:59] op_sel_hi:[0,1]
	v_pk_mul_f32 v[56:57], v[70:71], v[56:57] op_sel_hi:[0,1]
	s_waitcnt lgkmcnt(2)
	v_mfma_f32_16x16x32_bf16 v[138:141], v[158:161], v[168:171], v[138:141]
	ds_read_b128 v[158:161], v110 offset:62592
	ds_read_b128 v[168:171], v110 offset:62656
	s_andn2_b64 vcc, exec, s[20:21]
	s_waitcnt lgkmcnt(1)
	v_mfma_f32_16x16x32_bf16 v[138:141], v[146:149], v[158:161], v[138:141]
	s_waitcnt lgkmcnt(0)
	v_mfma_f32_16x16x32_bf16 v[138:141], v[150:153], v[168:171], v[138:141]
	s_nop 7
	v_cvt_pk_bf16_f32 v92, v138, v139
	v_cvt_pk_bf16_f32 v93, v140, v141
	ds_write_b64 v111, v[92:93]
	s_waitcnt lgkmcnt(0)
	s_barrier
	ds_read_b128 v[138:141], v110 offset:62464
	ds_read_b128 v[146:149], v110 offset:62528
	ds_read_b128 v[150:153], v109 offset:17408
	ds_read_b128 v[158:161], v109 offset:17472
	s_waitcnt lgkmcnt(1)
	v_mfma_f32_16x16x32_bf16 v[138:141], v[138:141], v[150:153], 0
	ds_read_b128 v[150:153], v110 offset:62592
	ds_read_b128 v[168:171], v110 offset:62656
	v_lshl_add_u64 v[92:93], v[86:87], 0, v[68:69]
	s_waitcnt lgkmcnt(2)
	v_mfma_f32_16x16x32_bf16 v[138:141], v[146:149], v[158:161], v[138:141]
	ds_read_b128 v[146:149], v109 offset:17536
	ds_read_b128 v[158:161], v109 offset:17600
	s_waitcnt lgkmcnt(1)
	v_mfma_f32_16x16x32_bf16 v[138:141], v[150:153], v[146:149], v[138:141]
	ds_read_b128 v[146:149], v112
	ds_read_b128 v[150:153], v112 offset:64
	s_waitcnt lgkmcnt(2)
	v_mfma_f32_16x16x32_bf16 v[138:141], v[168:171], v[158:161], v[138:141]
	ds_read_b128 v[158:161], v113 offset:53248
	ds_read_b128 v[168:171], v113 offset:53312
	s_waitcnt lgkmcnt(1)
	v_mfma_f32_16x16x32_bf16 v[138:141], v[146:149], v[158:161], v[138:141]
	s_waitcnt lgkmcnt(0)
	v_mfma_f32_16x16x32_bf16 v[138:141], v[150:153], v[168:171], v[138:141]
	s_nop 7
	v_cvt_pk_bf16_f32 v138, v138, v139
	v_cvt_pk_bf16_f32 v139, v140, v141
	global_store_dwordx2 v[92:93], v[138:139], off sc1
	ds_read_b128 v[138:141], v114 offset:34816
	ds_read_b128 v[146:149], v115
	ds_read_b128 v[150:153], v114 offset:34880
	ds_read_b128 v[158:161], v115 offset:64
	ds_read_b128 v[168:171], v116
	s_waitcnt lgkmcnt(3)
	v_mfma_f32_16x16x32_bf16 v[60:63], v[138:141], v[146:149], v[60:63]
	ds_read_b128 v[146:149], v117 offset:64
	s_waitcnt vmcnt(9)
	ds_write_b128 v118, v[24:27]
	ds_write_b128 v119, v[32:35]
	ds_write_b128 v120, v[36:39]
	ds_write_b128 v121, v[40:43]
	s_waitcnt lgkmcnt(5)
	v_mfma_f32_16x16x32_bf16 v[56:59], v[138:141], v[168:171], v[56:59]
	ds_write_b128 v122, v[44:47]
	ds_write_b128 v123, v[48:51]
	ds_write_b128 v124, v[52:55]
	v_mfma_f32_16x16x32_bf16 v[60:63], v[150:153], v[158:161], v[60:63]
	s_waitcnt lgkmcnt(7)
	v_mfma_f32_16x16x32_bf16 v[56:59], v[150:153], v[146:149], v[56:59]
	s_nop 5
	v_cvt_pk_bf16_f32 v92, v60, v61
	v_cvt_pk_bf16_f32 v93, v62, v63
	v_cvt_pk_bf16_f32 v138, v56, v57
	v_cvt_pk_bf16_f32 v139, v58, v59
	ds_write_b64 v125, v[92:93]
	ds_write_b64 v126, v[138:139]
	s_waitcnt lgkmcnt(0)
	s_barrier
	v_mov_b32_e32 v138, v71
	v_mov_b64_e32 v[92:93], v[88:89]
	s_cbranch_vccnz .Lscan_nl
	v_mov_b64_e32 v[88:89], v[172:173]
	v_mov_b32_e32 v71, v174
	v_add_co_u32_e32 v32, vcc, 0xc000, v102
	s_add_i32 s6, s4, s5
	s_nop 0
	v_addc_co_u32_e32 v33, vcc, 0, v103, vcc
	v_add_co_u32_e32 v36, vcc, 0xc000, v100
	s_add_i32 s6, s6, 3
	s_nop 0
	v_addc_co_u32_e32 v37, vcc, 0, v101, vcc
	v_add_co_u32_e32 v44, vcc, 0xc000, v98
	s_lshl_b64 s[20:21], s[6:7], 14
	s_nop 0
	v_addc_co_u32_e32 v45, vcc, 0, v99, vcc
	v_add_co_u32_e32 v48, vcc, 0xc000, v96
	s_add_u32 s20, s82, s20
	s_nop 0
	v_addc_co_u32_e32 v49, vcc, 0, v97, vcc
	s_addc_u32 s21, s83, s21
	v_add_co_u32_e32 v92, vcc, 0xc000, v94
	v_lshl_add_u64 v[24:25], v[64:65], 1, s[20:21]
	v_lshl_add_u64 v[40:41], v[66:67], 1, s[20:21]
	v_addc_co_u32_e32 v93, vcc, 0, v95, vcc
	global_load_dwordx4 v[24:27], v[24:25], off
	s_nop 0
	global_load_dwordx4 v[32:35], v[32:33], off
	s_nop 0
	global_load_dwordx4 v[36:39], v[36:37], off
	s_nop 0
	global_load_dwordx4 v[40:43], v[40:41], off
	s_nop 0
	global_load_dwordx4 v[44:47], v[44:45], off
	s_nop 0
	global_load_dwordx4 v[48:51], v[48:49], off
	s_nop 0
	global_load_dwordx4 v[52:55], v[72:73], off
	s_nop 0
	global_load_dwordx2 v[172:173], v[92:93], off
	s_nop 0
	global_load_dword v174, v69, s[10:11]
	s_branch .LBB0_576
.Lscan_nl:
	s_waitcnt vmcnt(0)
	v_mov_b64_e32 v[88:89], v[172:173]
	v_mov_b32_e32 v71, v174
	s_branch .LBB0_576
.Lscan_noE:
	s_waitcnt vmcnt(0)
	s_branch .LBB0_579
